# ctx attention softmax on raw scores: 1/8 scale folded into the exp2 constant, (s-m)*c pairs fused into one fma, 20 scale multiplies per tile removed (f32 re-association only)
# baseline (speedup 1.0000x reference)
.LBB0_239:
	s_barrier
	ds_write_b128 v104, v[44:47]
	ds_write_b128 v106, v[40:43]
	v_and_b32_e32 v223, 0xff, v160
	v_lshrrev_b32_e32 v224, 2, v223
	v_and_b32_e32 v225, 3, v223
	v_lshrrev_b32_e32 v226, 1, v225
	v_bfe_u32 v227, v224, 1, 1
	v_xor_b32_e32 v226, v226, v227
	v_lshlrev_b32_e32 v226, 6, v226
	v_and_b32_e32 v225, 1, v225
	v_lshl_or_b32 v226, v225, 5, v226
	v_lshl_add_u32 v226, v224, 7, v226
	v_add_u32_e32 v223, s78, v226
	v_and_b32_e32 v226, 63, v160
	v_lshrrev_b32_e32 v224, 5, v226
	v_bfe_u32 v227, v226, 2, 2
	v_lshl_add_u32 v224, v224, 2, v227
	v_lshlrev_b32_e32 v224, 7, v224
	v_bfe_u32 v227, v226, 3, 1
	v_lshl_or_b32 v224, v227, 6, v224
	v_bfe_u32 v227, v226, 4, 1
	v_lshl_or_b32 v224, v227, 5, v224
	v_and_b32_e32 v227, 3, v226
	v_lshl_or_b32 v224, v227, 3, v224
	v_add_u32_e32 v224, s78, v224
	v_xor_b32_e32 v225, 64, v224
	ds_write_b128 v223, v[36:39] offset:8192
	ds_write_b128 v223, v[32:35] offset:8208
	s_waitcnt lgkmcnt(0)
	s_barrier
	ds_read_b128 v[32:35], v107
	ds_read_b128 v[48:51], v107 offset:4096
	s_waitcnt lgkmcnt(1)
	v_mfma_f32_32x32x16_bf16 v[32:47], v[32:35], v[72:75], 0
	ds_read_b128 v[114:117], v108
	ds_read_b128 v[118:121], v108 offset:4096
	s_mov_b32 s6, 0x3e38aa3b
	s_mov_b32 s1, 0xf149f2ca
	v_add_u32_e32 v135, 0x2000, v111
	s_add_i32 s5, s5, 64
	s_cmpk_lg_i32 s5, 0x100
	s_waitcnt lgkmcnt(2)
	v_mfma_f32_32x32x16_bf16 v[48:63], v[48:51], v[72:75], 0
	s_waitcnt lgkmcnt(1)
	v_mfma_f32_32x32x16_bf16 v[32:47], v[114:117], v[64:67], v[32:47]
	ds_read_b128 v[114:117], v109 offset:4096
	s_waitcnt lgkmcnt(1)
	v_mfma_f32_32x32x16_bf16 v[48:63], v[118:121], v[64:67], v[48:63]
	s_waitcnt lgkmcnt(0)
	v_mfma_f32_32x32x16_bf16 v[48:63], v[114:117], v[68:71], v[48:63]
	ds_read_b128 v[114:117], v110 offset:4096
	s_waitcnt lgkmcnt(0)
	v_mfma_f32_32x32x16_bf16 v[48:63], v[114:117], v[76:79], v[48:63]
	ds_read_b128 v[114:117], v109
	ds_read_b128 v[118:121], v110
	s_waitcnt lgkmcnt(1)
	v_mfma_f32_32x32x16_bf16 v[32:47], v[114:117], v[68:71], v[32:47]
	s_nop 7
	s_nop 0
	s_nop 0
	s_nop 0
	s_nop 0
	s_nop 0
	s_nop 0
	s_nop 0
	s_nop 0
	s_nop 0
	s_nop 0
	s_waitcnt lgkmcnt(0)
	v_mfma_f32_32x32x16_bf16 v[32:47], v[118:121], v[76:79], v[32:47]
	s_nop 0
	s_nop 0
	s_nop 9
	v_mov_b32_e32 v114, v32
	v_mov_b32_e32 v115, v33
	s_nop 0
	v_max3_f32 v32, v114, s1, v115
	s_nop 0
	v_max3_f32 v32, v32, v34, v35
	s_nop 0
	v_max3_f32 v32, v32, v36, v37
	s_nop 0
	v_max3_f32 v32, v32, v38, v39
	s_nop 0
	v_max3_f32 v32, v32, v40, v41
	s_nop 0
	v_max3_f32 v32, v32, v42, v43
	s_nop 0
	v_max3_f32 v32, v32, v44, v45
	v_max3_f32 v32, v32, v46, v47
	v_max3_f32 v32, v32, v48, v49
	v_max3_f32 v32, v32, v50, v51
	v_max3_f32 v32, v32, v52, v53
	v_max3_f32 v32, v32, v54, v55
	v_max3_f32 v32, v32, v56, v57
	v_max3_f32 v32, v32, v58, v59
	v_max3_f32 v32, v32, v60, v61
	v_max3_f32 v32, v32, v62, v63
	ds_bpermute_b32 v33, v100, v32
	v_cmp_lt_f32_e32 vcc, s86, v115
	s_waitcnt lgkmcnt(0)
	v_max3_f32 v33, v112, v32, v33
	v_mul_f32_e32 v229, 0xbe38aa3b, v33
	v_fma_f32 v113, v115, s6, v229
	v_fma_f32 v32, v112, s6, v229
	v_fma_f32 v112, v114, s6, v229
	s_nop 0
	v_exp_f32_e32 v113, v113
	s_nop 0
	v_fma_f32 v116, v35, s6, v229
	v_exp_f32_e32 v112, v112
	v_fma_f32 v115, v34, s6, v229
	s_nop 0
	v_exp_f32_e32 v116, v116
	s_nop 0
	v_exp_f32_e32 v115, v115
	v_cndmask_b32_e32 v113, 0, v113, vcc
	v_cmp_lt_f32_e32 vcc, s86, v114
	s_nop 0
	v_exp_f32_e32 v32, v32
	v_cndmask_b32_e32 v112, 0, v112, vcc
	v_cmp_lt_f32_e32 vcc, s86, v35
	v_add_f32_e32 v114, 0, v112
	v_add_f32_e32 v114, v113, v114
	v_cndmask_b32_e32 v116, 0, v116, vcc
	v_cmp_lt_f32_e32 vcc, s86, v34
	v_fma_f32 v35, v36, s6, v229
	s_nop 0
	v_cndmask_b32_e32 v115, 0, v115, vcc
	v_add_f32_e32 v34, v115, v114
	v_fma_f32 v114, v37, s6, v229
	s_nop 0
	v_exp_f32_e32 v114, v114
	v_exp_f32_e32 v35, v35
	v_cmp_lt_f32_e32 vcc, s86, v37
	v_add_f32_e32 v34, v116, v34
	v_pk_mul_f32 v[30:31], v[30:31], v[32:33] op_sel_hi:[1,0]
	v_cndmask_b32_e32 v114, 0, v114, vcc
	v_cmp_lt_f32_e32 vcc, s86, v36
	v_fma_f32 v36, v39, s6, v229
	s_nop 0
	v_cndmask_b32_e32 v117, 0, v35, vcc
	v_fma_f32 v35, v38, s6, v229
	v_exp_f32_e32 v36, v36
	s_nop 0
	v_exp_f32_e32 v35, v35
	v_cmp_lt_f32_e32 vcc, s86, v39
	v_add_f32_e32 v34, v117, v34
	v_add_f32_e32 v34, v114, v34
	v_cndmask_b32_e32 v118, 0, v36, vcc
	v_cmp_lt_f32_e32 vcc, s86, v38
	v_fma_f32 v36, v41, s6, v229
	s_nop 0
	v_cndmask_b32_e32 v119, 0, v35, vcc
	v_fma_f32 v35, v40, s6, v229
	v_exp_f32_e32 v36, v36
	s_nop 0
	v_exp_f32_e32 v35, v35
	v_cmp_lt_f32_e32 vcc, s86, v41
	v_add_f32_e32 v34, v119, v34
	v_add_f32_e32 v34, v118, v34
	v_cndmask_b32_e32 v120, 0, v36, vcc
	v_cmp_lt_f32_e32 vcc, s86, v40
	v_fma_f32 v36, v43, s6, v229
	s_nop 0
	v_cndmask_b32_e32 v121, 0, v35, vcc
	v_fma_f32 v35, v42, s6, v229
	v_exp_f32_e32 v36, v36
	s_nop 0
	v_exp_f32_e32 v35, v35
	v_cmp_lt_f32_e32 vcc, s86, v43
	v_add_f32_e32 v34, v121, v34
	v_add_f32_e32 v34, v120, v34
	v_cndmask_b32_e32 v122, 0, v36, vcc
	v_cmp_lt_f32_e32 vcc, s86, v42
	v_fma_f32 v36, v45, s6, v229
	s_nop 0
	v_cndmask_b32_e32 v123, 0, v35, vcc
	v_fma_f32 v35, v44, s6, v229
	v_exp_f32_e32 v36, v36
	s_nop 0
	v_exp_f32_e32 v35, v35
	v_cmp_lt_f32_e32 vcc, s86, v45
	v_add_f32_e32 v34, v123, v34
	v_add_f32_e32 v34, v122, v34
	v_cndmask_b32_e32 v124, 0, v36, vcc
	v_cmp_lt_f32_e32 vcc, s86, v44
	v_fma_f32 v36, v47, s6, v229
	s_nop 0
	v_cndmask_b32_e32 v125, 0, v35, vcc
	v_fma_f32 v35, v46, s6, v229
	v_exp_f32_e32 v36, v36
	s_nop 0
	v_exp_f32_e32 v35, v35
	v_cmp_lt_f32_e32 vcc, s86, v47
	v_add_f32_e32 v34, v125, v34
	v_add_f32_e32 v34, v124, v34
	v_cndmask_b32_e32 v47, 0, v36, vcc
	v_cmp_lt_f32_e32 vcc, s86, v46
	v_fma_f32 v36, v49, s6, v229
	s_nop 0
	v_cndmask_b32_e32 v46, 0, v35, vcc
	v_fma_f32 v35, v48, s6, v229
	v_exp_f32_e32 v36, v36
	s_nop 0
	v_exp_f32_e32 v35, v35
	v_cmp_lt_f32_e32 vcc, s86, v49
	v_add_f32_e32 v34, v46, v34
	v_add_f32_e32 v34, v47, v34
	v_cndmask_b32_e32 v49, 0, v36, vcc
	v_cmp_lt_f32_e32 vcc, s86, v48
	v_fma_f32 v36, v51, s6, v229
	s_nop 0
	v_cndmask_b32_e32 v48, 0, v35, vcc
	v_fma_f32 v35, v50, s6, v229
	v_exp_f32_e32 v36, v36
	s_nop 0
	v_exp_f32_e32 v35, v35
	v_cmp_lt_f32_e32 vcc, s86, v51
	v_add_f32_e32 v34, v48, v34
	v_add_f32_e32 v34, v49, v34
	v_cndmask_b32_e32 v51, 0, v36, vcc
	v_cmp_lt_f32_e32 vcc, s86, v50
	v_fma_f32 v36, v53, s6, v229
	s_nop 0
	v_cndmask_b32_e32 v50, 0, v35, vcc
	v_fma_f32 v35, v52, s6, v229
	v_exp_f32_e32 v36, v36
	s_nop 0
	v_exp_f32_e32 v35, v35
	v_cmp_lt_f32_e32 vcc, s86, v53
	v_add_f32_e32 v34, v50, v34
	v_add_f32_e32 v34, v51, v34
	v_cndmask_b32_e32 v53, 0, v36, vcc
	v_cmp_lt_f32_e32 vcc, s86, v52
	v_fma_f32 v36, v55, s6, v229
	s_nop 0
	v_cndmask_b32_e32 v52, 0, v35, vcc
	v_fma_f32 v35, v54, s6, v229
	v_exp_f32_e32 v36, v36
	s_nop 0
	v_exp_f32_e32 v35, v35
	v_cmp_lt_f32_e32 vcc, s86, v55
	v_add_f32_e32 v34, v52, v34
	v_add_f32_e32 v34, v53, v34
	v_cndmask_b32_e32 v55, 0, v36, vcc
	v_cmp_lt_f32_e32 vcc, s86, v54
	v_fma_f32 v36, v57, s6, v229
	s_nop 0
	v_cndmask_b32_e32 v54, 0, v35, vcc
	v_fma_f32 v35, v56, s6, v229
	v_exp_f32_e32 v36, v36
	s_nop 0
	v_exp_f32_e32 v35, v35
	v_cmp_lt_f32_e32 vcc, s86, v57
	v_add_f32_e32 v34, v54, v34
	v_add_f32_e32 v34, v55, v34
	v_cndmask_b32_e32 v57, 0, v36, vcc
	v_cmp_lt_f32_e32 vcc, s86, v56
	v_fma_f32 v36, v59, s6, v229
	s_nop 0
	v_cndmask_b32_e32 v56, 0, v35, vcc
	v_fma_f32 v35, v58, s6, v229
	v_exp_f32_e32 v36, v36
	s_nop 0
	v_exp_f32_e32 v35, v35
	v_cmp_lt_f32_e32 vcc, s86, v59
	v_add_f32_e32 v34, v56, v34
	v_add_f32_e32 v34, v57, v34
	v_cndmask_b32_e32 v59, 0, v36, vcc
	v_cmp_lt_f32_e32 vcc, s86, v58
	v_cvt_pk_bf16_f32 v38, v112, v113
	v_add_u32_e32 v112, 0x3000, v111
	v_cndmask_b32_e32 v58, 0, v35, vcc
	v_add_f32_e32 v34, v58, v34
	v_add_f32_e32 v126, v59, v34
	v_fma_f32 v34, v60, s6, v229
	v_mov_b32_e32 v127, v34
	ds_read_b64_tr_b16 v[34:35], v224 offset:8192
	ds_read_b64_tr_b16 v[36:37], v224 offset:9216
	ds_read_b64_tr_b16 v[42:43], v225 offset:8192
	ds_read_b64_tr_b16 v[44:45], v225 offset:9216
	v_pk_mul_f32 v[28:29], v[28:29], v[32:33] op_sel_hi:[1,0]
	v_pk_mul_f32 v[26:27], v[26:27], v[32:33] op_sel_hi:[1,0]
	v_pk_mul_f32 v[24:25], v[24:25], v[32:33] op_sel_hi:[1,0]
	v_pk_mul_f32 v[22:23], v[22:23], v[32:33] op_sel_hi:[1,0]
	v_pk_mul_f32 v[20:21], v[20:21], v[32:33] op_sel_hi:[1,0]
	v_pk_mul_f32 v[18:19], v[18:19], v[32:33] op_sel_hi:[1,0]
	v_pk_mul_f32 v[16:17], v[16:17], v[32:33] op_sel_hi:[1,0]
	v_cvt_pk_bf16_f32 v39, v115, v116
	v_cvt_pk_bf16_f32 v40, v117, v114
	v_cvt_pk_bf16_f32 v41, v119, v118
	v_fma_f32 v134, v61, s6, v229
	v_pk_mul_f32 v[14:15], v[14:15], v[32:33] op_sel_hi:[1,0]
	s_waitcnt lgkmcnt(2)
	v_mfma_f32_32x32x16_bf16 v[16:31], v[34:37], v[38:41], v[16:31]
	ds_read_b64_tr_b16 v[34:35], v224 offset:10240
	ds_read_b64_tr_b16 v[36:37], v224 offset:11264
	v_mul_f32_e64 v12, v12, v32
	v_mul_f32_e64 v13, v13, v32
	v_mul_f32_e64 v10, v10, v32
	v_mul_f32_e64 v11, v11, v32
	v_pk_mul_f32 v[8:9], v[8:9], v[32:33] op_sel_hi:[1,0]
	v_pk_mul_f32 v[6:7], v[6:7], v[32:33] op_sel_hi:[1,0]
	v_pk_mul_f32 v[4:5], v[4:5], v[32:33] op_sel_hi:[1,0]
	v_pk_mul_f32 v[2:3], v[2:3], v[32:33] op_sel_hi:[1,0]
	v_pk_mul_f32 v[0:1], v[0:1], v[32:33] op_sel_hi:[1,0]
	v_cmp_lt_f32_e32 vcc, s86, v61
	v_fma_f32 v61, v62, s6, v229
	s_waitcnt lgkmcnt(2)
	v_mfma_f32_32x32x16_bf16 v[0:15], v[42:45], v[38:41], v[0:15]
	v_mov_b32_e32 v38, v134
	v_exp_f32_e32 v113, v38
	v_cvt_pk_bf16_f32 v38, v121, v120
	v_cvt_pk_bf16_f32 v39, v123, v122
	v_cvt_pk_bf16_f32 v40, v125, v124
	v_cvt_pk_bf16_f32 v41, v46, v47
	ds_read_b64_tr_b16 v[42:43], v225 offset:10240
	ds_read_b64_tr_b16 v[44:45], v225 offset:11264
	v_cndmask_b32_e32 v46, 0, v113, vcc
	s_waitcnt lgkmcnt(2)
	v_mfma_f32_32x32x16_bf16 v[16:31], v[34:37], v[38:41], v[16:31]
	v_exp_f32_e32 v34, v127
	v_cmp_lt_f32_e32 vcc, s86, v60
	s_nop 1
	v_cndmask_b32_e32 v47, 0, v34, vcc
	ds_read_b64_tr_b16 v[34:35], v224 offset:12288
	ds_read_b64_tr_b16 v[36:37], v224 offset:13312
	v_cmp_lt_f32_e32 vcc, s86, v63
	s_waitcnt lgkmcnt(2)
	v_mfma_f32_32x32x16_bf16 v[0:15], v[42:45], v[38:41], v[0:15]
	ds_read_b64_tr_b16 v[42:43], v225 offset:12288
	ds_read_b64_tr_b16 v[44:45], v225 offset:13312
	v_cvt_pk_bf16_f32 v38, v48, v49
	v_cvt_pk_bf16_f32 v39, v50, v51
	v_cvt_pk_bf16_f32 v40, v52, v53
	v_cvt_pk_bf16_f32 v41, v54, v55
	v_add_f32_e32 v60, v47, v126
	v_add_f32_e32 v60, v46, v60
	s_waitcnt lgkmcnt(2)
	v_mfma_f32_32x32x16_bf16 v[16:31], v[34:37], v[38:41], v[16:31]
	v_fma_f32 v34, v63, s6, v229
	s_nop 0
	v_exp_f32_e32 v34, v34
	v_mov_b32_e32 v35, v61
	v_exp_f32_e32 v48, v35
	v_cndmask_b32_e32 v49, 0, v34, vcc
	s_waitcnt lgkmcnt(0)
	v_mfma_f32_32x32x16_bf16 v[0:15], v[42:45], v[38:41], v[0:15]
	ds_read_b64_tr_b16 v[34:35], v224 offset:14336
	ds_read_b64_tr_b16 v[36:37], v224 offset:15360
	ds_read_b64_tr_b16 v[42:43], v225 offset:14336
	ds_read_b64_tr_b16 v[44:45], v225 offset:15360
	v_cmp_lt_f32_e32 vcc, s86, v62
	v_cvt_pk_bf16_f32 v38, v56, v57
	v_cvt_pk_bf16_f32 v39, v58, v59
	v_cndmask_b32_e32 v41, 0, v48, vcc
	v_add_f32_e32 v48, v41, v60
	v_cvt_pk_bf16_f32 v40, v47, v46
	v_cvt_pk_bf16_f32 v41, v41, v49
	s_waitcnt lgkmcnt(2)
	s_nop 0
	v_mfma_f32_32x32x16_bf16 v[16:31], v[34:37], v[38:41], v[16:31]
	v_add_f32_e32 v34, v49, v48
	ds_bpermute_b32 v35, v100, v34
	s_waitcnt lgkmcnt(0)
	v_add_f32_e32 v34, v34, v35
	v_mfma_f32_32x32x16_bf16 v[0:15], v[42:45], v[38:41], v[0:15]
	v_fmac_f32_e32 v34, v105, v32
	s_cbranch_scc1 .LBB0_237
	v_mul_f32_e32 v33, 0x3e000000, v33
	v_max_f32_e32 v32, v99, v99
	v_max_f32_e32 v35, v33, v33
	v_max_f32_e32 v32, v35, v32
	v_sub_f32_e32 v33, v33, v32
	v_sub_f32_e32 v32, v99, v32
	v_mul_f32_e32 v33, 0x3fb8aa3b, v33
	v_mul_f32_e32 v32, 0x3fb8aa3b, v32
	v_exp_f32_e32 v33, v33
	v_exp_f32_e32 v32, v32
	s_lshl_b32 s92, s4, 1
	v_lshlrev_b32_e32 v128, 3, v98
	v_fmac_f32_e32 v32, v33, v34
	v_div_scale_f32 v34, s[0:1], v32, v32, v33
	v_rcp_f32_e32 v35, v34
	v_readlane_b32 s0, v254, 43
	v_readlane_b32 s1, v254, 44
	v_fma_f32 v36, -v34, v35, 1.0
	v_fmac_f32_e32 v35, v36, v35
	v_div_scale_f32 v36, vcc, v33, v32, v33
	v_mul_f32_e32 v37, v36, v35
	v_fma_f32 v38, -v34, v37, v36
	v_fmac_f32_e32 v37, v38, v35
	v_fma_f32 v34, -v34, v37, v36
	v_div_fmas_f32 v34, v34, v35, v37
	v_div_fixup_f32 v32, v34, v32, v33
	v_lshlrev_b64 v[34:35], 11, v[96:97]
	v_lshl_add_u64 v[34:35], s[0:1], 0, v[34:35]
	v_lshl_add_u64 v[34:35], v[34:35], 0, s[92:93]
	v_pk_mul_f32 v[16:17], v[16:17], v[32:33] op_sel_hi:[1,0]
	v_pk_mul_f32 v[18:19], v[18:19], v[32:33] op_sel_hi:[1,0]
	v_cvt_pk_bf16_f32 v16, v16, v17
	v_cvt_pk_bf16_f32 v17, v18, v19
	v_lshl_add_u64 v[18:19], v[34:35], 0, v[128:129]
	s_mov_b64 s[0:1], 0x153ca600
	v_lshl_add_u64 v[34:35], v[18:19], 0, s[0:1]
	s_mov_b32 s0, 0x153ca000
	v_add_co_u32_e32 v18, vcc, s0, v18
	v_pk_mul_f32 v[0:1], v[0:1], v[32:33] op_sel_hi:[1,0]
	v_pk_mul_f32 v[2:3], v[2:3], v[32:33] op_sel_hi:[1,0]
	v_addc_co_u32_e32 v19, vcc, 0, v19, vcc
	v_cvt_pk_bf16_f32 v0, v0, v1
	v_cvt_pk_bf16_f32 v1, v2, v3
	global_store_dwordx2 v[18:19], v[16:17], off offset:1536
	v_pk_mul_f32 v[16:17], v[20:21], v[32:33] op_sel_hi:[1,0]
	v_pk_mul_f32 v[18:19], v[22:23], v[32:33] op_sel_hi:[1,0]
	global_store_dwordx2 v[34:35], v[0:1], off offset:64
	v_pk_mul_f32 v[0:1], v[4:5], v[32:33] op_sel_hi:[1,0]
	v_pk_mul_f32 v[2:3], v[6:7], v[32:33] op_sel_hi:[1,0]
	v_cvt_pk_bf16_f32 v16, v16, v17
	v_cvt_pk_bf16_f32 v17, v18, v19
	v_cvt_pk_bf16_f32 v0, v0, v1
	v_cvt_pk_bf16_f32 v1, v2, v3
	global_store_dwordx2 v[34:35], v[16:17], off offset:16
	v_pk_mul_f32 v[16:17], v[24:25], v[32:33] op_sel_hi:[1,0]
	v_pk_mul_f32 v[18:19], v[26:27], v[32:33] op_sel_hi:[1,0]
	global_store_dwordx2 v[34:35], v[0:1], off offset:80
	v_pk_mul_f32 v[0:1], v[8:9], v[32:33] op_sel_hi:[1,0]
	v_pk_mul_f32 v[2:3], v[10:11], v[32:33] op_sel_hi:[1,0]
	v_cvt_pk_bf16_f32 v16, v16, v17
	v_cvt_pk_bf16_f32 v17, v18, v19
	v_cvt_pk_bf16_f32 v0, v0, v1
	v_cvt_pk_bf16_f32 v1, v2, v3
	global_store_dwordx2 v[34:35], v[16:17], off offset:32
	v_pk_mul_f32 v[16:17], v[28:29], v[32:33] op_sel_hi:[1,0]
	v_pk_mul_f32 v[18:19], v[30:31], v[32:33] op_sel_hi:[1,0]
	global_store_dwordx2 v[34:35], v[0:1], off offset:96
	v_pk_mul_f32 v[0:1], v[12:13], v[32:33] op_sel_hi:[1,0]
	v_pk_mul_f32 v[2:3], v[14:15], v[32:33] op_sel_hi:[1,0]
	v_cvt_pk_bf16_f32 v16, v16, v17
	v_cvt_pk_bf16_f32 v17, v18, v19
	v_cvt_pk_bf16_f32 v0, v0, v1
	v_cvt_pk_bf16_f32 v1, v2, v3
	global_store_dwordx2 v[34:35], v[16:17], off offset:48
	global_store_dwordx2 v[34:35], v[0:1], off offset:112
	s_barrier
	s_mov_b64 s[0:1], 0

.LBB0_245:
	s_barrier
	ds_write_b128 v104, v[44:47]
	ds_write_b128 v105, v[40:43]
	v_and_b32_e32 v223, 0xff, v160
	v_lshrrev_b32_e32 v224, 2, v223
	v_and_b32_e32 v225, 3, v223
	v_lshrrev_b32_e32 v226, 1, v225
	v_bfe_u32 v227, v224, 1, 1
	v_xor_b32_e32 v226, v226, v227
	v_lshlrev_b32_e32 v226, 6, v226
	v_and_b32_e32 v225, 1, v225
	v_lshl_or_b32 v226, v225, 5, v226
	v_lshl_add_u32 v226, v224, 7, v226
	v_add_u32_e32 v223, s78, v226
	v_and_b32_e32 v226, 63, v160
	v_lshrrev_b32_e32 v224, 5, v226
	v_bfe_u32 v227, v226, 2, 2
	v_lshl_add_u32 v224, v224, 2, v227
	v_lshlrev_b32_e32 v224, 7, v224
	v_bfe_u32 v227, v226, 3, 1
	v_lshl_or_b32 v224, v227, 6, v224
	v_bfe_u32 v227, v226, 4, 1
	v_lshl_or_b32 v224, v227, 5, v224
	v_and_b32_e32 v227, 3, v226
	v_lshl_or_b32 v224, v227, 3, v224
	v_add_u32_e32 v224, s78, v224
	v_xor_b32_e32 v225, 64, v224
	ds_write_b128 v223, v[36:39] offset:8192
	ds_write_b128 v223, v[32:35] offset:8208
	s_waitcnt lgkmcnt(0)
	s_barrier
	ds_read_b128 v[32:35], v106
	ds_read_b128 v[48:51], v106 offset:4096
	s_waitcnt lgkmcnt(1)
	v_mfma_f32_32x32x16_bf16 v[32:47], v[32:35], v[64:67], 0
	ds_read_b128 v[114:117], v108
	ds_read_b128 v[118:121], v108 offset:4096
	s_mov_b32 s6, 0x3e38aa3b
	s_mov_b32 s5, 0xf149f2ca
	v_add_u32_e32 v134, 0x2000, v111
	s_add_u32 s0, s0, 0x74000
	s_addc_u32 s1, s1, 0
	s_cmp_lg_u32 s0, 0x1d0000
	s_waitcnt lgkmcnt(2)
	v_mfma_f32_32x32x16_bf16 v[48:63], v[48:51], v[64:67], 0
	s_waitcnt lgkmcnt(1)
	v_mfma_f32_32x32x16_bf16 v[32:47], v[114:117], v[68:71], v[32:47]
	ds_read_b128 v[114:117], v109 offset:4096
	s_waitcnt lgkmcnt(1)
	v_mfma_f32_32x32x16_bf16 v[48:63], v[118:121], v[68:71], v[48:63]
	s_waitcnt lgkmcnt(0)
	v_mfma_f32_32x32x16_bf16 v[48:63], v[114:117], v[72:75], v[48:63]
	ds_read_b128 v[114:117], v110 offset:4096
	s_waitcnt lgkmcnt(0)
	v_mfma_f32_32x32x16_bf16 v[48:63], v[114:117], v[76:79], v[48:63]
	ds_read_b128 v[114:117], v109
	ds_read_b128 v[118:121], v110
	s_waitcnt lgkmcnt(1)
	v_mfma_f32_32x32x16_bf16 v[32:47], v[114:117], v[72:75], v[32:47]
	s_nop 7
	s_nop 0
	s_nop 0
	s_nop 0
	s_nop 0
	s_nop 0
	s_nop 0
	s_nop 0
	s_nop 0
	s_nop 0
	s_nop 0
	s_waitcnt lgkmcnt(0)
	v_mfma_f32_32x32x16_bf16 v[32:47], v[118:121], v[76:79], v[32:47]
	s_nop 0
	s_nop 0
	s_nop 9
	v_mov_b32_e32 v114, v32
	v_mov_b32_e32 v115, v33
	s_nop 0
	v_max3_f32 v32, v114, s5, v115
	s_nop 0
	v_max3_f32 v32, v32, v34, v35
	s_nop 0
	v_max3_f32 v32, v32, v36, v37
	s_nop 0
	v_max3_f32 v32, v32, v38, v39
	s_nop 0
	v_max3_f32 v32, v32, v40, v41
	s_nop 0
	v_max3_f32 v32, v32, v42, v43
	s_nop 0
	v_max3_f32 v32, v32, v44, v45
	v_max3_f32 v32, v32, v46, v47
	v_max3_f32 v32, v32, v48, v49
	v_max3_f32 v32, v32, v50, v51
	v_max3_f32 v32, v32, v52, v53
	v_max3_f32 v32, v32, v54, v55
	v_max3_f32 v32, v32, v56, v57
	v_max3_f32 v32, v32, v58, v59
	v_max3_f32 v32, v32, v60, v61
	v_max3_f32 v32, v32, v62, v63
	ds_bpermute_b32 v33, v101, v32
	v_cmp_lt_f32_e32 vcc, s86, v115
	s_waitcnt lgkmcnt(0)
	v_max3_f32 v33, v112, v32, v33
	v_mul_f32_e32 v229, 0xbe38aa3b, v33
	v_fma_f32 v113, v115, s6, v229
	v_fma_f32 v32, v112, s6, v229
	v_fma_f32 v112, v114, s6, v229
	s_nop 0
	v_exp_f32_e32 v113, v113
	s_nop 0
	v_fma_f32 v116, v35, s6, v229
	v_exp_f32_e32 v112, v112
	v_fma_f32 v115, v34, s6, v229
	s_nop 0
	v_exp_f32_e32 v116, v116
	s_nop 0
	v_exp_f32_e32 v115, v115
	v_cndmask_b32_e32 v113, 0, v113, vcc
	v_cmp_lt_f32_e32 vcc, s86, v114
	s_nop 0
	v_exp_f32_e32 v32, v32
	v_cndmask_b32_e32 v112, 0, v112, vcc
	v_cmp_lt_f32_e32 vcc, s86, v35
	v_add_f32_e32 v114, 0, v112
	v_add_f32_e32 v114, v113, v114
	v_cndmask_b32_e32 v116, 0, v116, vcc
	v_cmp_lt_f32_e32 vcc, s86, v34
	v_fma_f32 v35, v36, s6, v229
	s_nop 0
	v_cndmask_b32_e32 v115, 0, v115, vcc
	v_add_f32_e32 v34, v115, v114
	v_fma_f32 v114, v37, s6, v229
	s_nop 0
	v_exp_f32_e32 v114, v114
	v_exp_f32_e32 v35, v35
	v_cmp_lt_f32_e32 vcc, s86, v37
	v_add_f32_e32 v34, v116, v34
	v_pk_mul_f32 v[30:31], v[30:31], v[32:33] op_sel_hi:[1,0]
	v_cndmask_b32_e32 v114, 0, v114, vcc
	v_cmp_lt_f32_e32 vcc, s86, v36
	v_fma_f32 v36, v39, s6, v229
	s_nop 0
	v_cndmask_b32_e32 v117, 0, v35, vcc
	v_fma_f32 v35, v38, s6, v229
	v_exp_f32_e32 v36, v36
	s_nop 0
	v_exp_f32_e32 v35, v35
	v_cmp_lt_f32_e32 vcc, s86, v39
	v_add_f32_e32 v34, v117, v34
	v_add_f32_e32 v34, v114, v34
	v_cndmask_b32_e32 v118, 0, v36, vcc
	v_cmp_lt_f32_e32 vcc, s86, v38
	v_fma_f32 v36, v41, s6, v229
	s_nop 0
	v_cndmask_b32_e32 v119, 0, v35, vcc
	v_fma_f32 v35, v40, s6, v229
	v_exp_f32_e32 v36, v36
	s_nop 0
	v_exp_f32_e32 v35, v35
	v_cmp_lt_f32_e32 vcc, s86, v41
	v_add_f32_e32 v34, v119, v34
	v_add_f32_e32 v34, v118, v34
	v_cndmask_b32_e32 v120, 0, v36, vcc
	v_cmp_lt_f32_e32 vcc, s86, v40
	v_fma_f32 v36, v43, s6, v229
	s_nop 0
	v_cndmask_b32_e32 v121, 0, v35, vcc
	v_fma_f32 v35, v42, s6, v229
	v_exp_f32_e32 v36, v36
	s_nop 0
	v_exp_f32_e32 v35, v35
	v_cmp_lt_f32_e32 vcc, s86, v43
	v_add_f32_e32 v34, v121, v34
	v_add_f32_e32 v34, v120, v34
	v_cndmask_b32_e32 v122, 0, v36, vcc
	v_cmp_lt_f32_e32 vcc, s86, v42
	v_fma_f32 v36, v45, s6, v229
	s_nop 0
	v_cndmask_b32_e32 v123, 0, v35, vcc
	v_fma_f32 v35, v44, s6, v229
	v_exp_f32_e32 v36, v36
	s_nop 0
	v_exp_f32_e32 v35, v35
	v_cmp_lt_f32_e32 vcc, s86, v45
	v_add_f32_e32 v34, v123, v34
	v_add_f32_e32 v34, v122, v34
	v_cndmask_b32_e32 v124, 0, v36, vcc
	v_cmp_lt_f32_e32 vcc, s86, v44
	v_fma_f32 v36, v47, s6, v229
	s_nop 0
	v_cndmask_b32_e32 v125, 0, v35, vcc
	v_fma_f32 v35, v46, s6, v229
	v_exp_f32_e32 v36, v36
	s_nop 0
	v_exp_f32_e32 v35, v35
	v_cmp_lt_f32_e32 vcc, s86, v47
	v_add_f32_e32 v34, v125, v34
	v_add_f32_e32 v34, v124, v34
	v_cndmask_b32_e32 v47, 0, v36, vcc
	v_cmp_lt_f32_e32 vcc, s86, v46
	v_fma_f32 v36, v49, s6, v229
	s_nop 0
	v_cndmask_b32_e32 v46, 0, v35, vcc
	v_fma_f32 v35, v48, s6, v229
	v_exp_f32_e32 v36, v36
	s_nop 0
	v_exp_f32_e32 v35, v35
	v_cmp_lt_f32_e32 vcc, s86, v49
	v_add_f32_e32 v34, v46, v34
	v_add_f32_e32 v34, v47, v34
	v_cndmask_b32_e32 v49, 0, v36, vcc
	v_cmp_lt_f32_e32 vcc, s86, v48
	v_fma_f32 v36, v51, s6, v229
	s_nop 0
	v_cndmask_b32_e32 v48, 0, v35, vcc
	v_fma_f32 v35, v50, s6, v229
	v_exp_f32_e32 v36, v36
	s_nop 0
	v_exp_f32_e32 v35, v35
	v_cmp_lt_f32_e32 vcc, s86, v51
	v_add_f32_e32 v34, v48, v34
	v_add_f32_e32 v34, v49, v34
	v_cndmask_b32_e32 v51, 0, v36, vcc
	v_cmp_lt_f32_e32 vcc, s86, v50
	v_fma_f32 v36, v53, s6, v229
	s_nop 0
	v_cndmask_b32_e32 v50, 0, v35, vcc
	v_fma_f32 v35, v52, s6, v229
	v_exp_f32_e32 v36, v36
	s_nop 0
	v_exp_f32_e32 v35, v35
	v_cmp_lt_f32_e32 vcc, s86, v53
	v_add_f32_e32 v34, v50, v34
	v_add_f32_e32 v34, v51, v34
	v_cndmask_b32_e32 v53, 0, v36, vcc
	v_cmp_lt_f32_e32 vcc, s86, v52
	v_fma_f32 v36, v55, s6, v229
	s_nop 0
	v_cndmask_b32_e32 v52, 0, v35, vcc
	v_fma_f32 v35, v54, s6, v229
	v_exp_f32_e32 v36, v36
	s_nop 0
	v_exp_f32_e32 v35, v35
	v_cmp_lt_f32_e32 vcc, s86, v55
	v_add_f32_e32 v34, v52, v34
	v_add_f32_e32 v34, v53, v34
	v_cndmask_b32_e32 v55, 0, v36, vcc
	v_cmp_lt_f32_e32 vcc, s86, v54
	v_fma_f32 v36, v57, s6, v229
	s_nop 0
	v_cndmask_b32_e32 v54, 0, v35, vcc
	v_fma_f32 v35, v56, s6, v229
	v_exp_f32_e32 v36, v36
	s_nop 0
	v_exp_f32_e32 v35, v35
	v_cmp_lt_f32_e32 vcc, s86, v57
	v_add_f32_e32 v34, v54, v34
	v_add_f32_e32 v34, v55, v34
	v_cndmask_b32_e32 v57, 0, v36, vcc
	v_cmp_lt_f32_e32 vcc, s86, v56
	v_fma_f32 v36, v59, s6, v229
	s_nop 0
	v_cndmask_b32_e32 v56, 0, v35, vcc
	v_fma_f32 v35, v58, s6, v229
	v_exp_f32_e32 v36, v36
	s_nop 0
	v_exp_f32_e32 v35, v35
	v_cmp_lt_f32_e32 vcc, s86, v59
	v_add_f32_e32 v34, v56, v34
	v_add_f32_e32 v34, v57, v34
	v_cndmask_b32_e32 v59, 0, v36, vcc
	v_cmp_lt_f32_e32 vcc, s86, v58
	v_cvt_pk_bf16_f32 v38, v112, v113
	v_add_u32_e32 v112, 0x3000, v111
	v_cndmask_b32_e32 v58, 0, v35, vcc
	v_add_f32_e32 v34, v58, v34
	v_add_f32_e32 v126, v59, v34
	v_fma_f32 v34, v60, s6, v229
	v_mov_b32_e32 v127, v34
	ds_read_b64_tr_b16 v[34:35], v224 offset:8192
	ds_read_b64_tr_b16 v[36:37], v224 offset:9216
	ds_read_b64_tr_b16 v[42:43], v225 offset:8192
	ds_read_b64_tr_b16 v[44:45], v225 offset:9216
	v_pk_mul_f32 v[28:29], v[28:29], v[32:33] op_sel_hi:[1,0]
	v_pk_mul_f32 v[26:27], v[26:27], v[32:33] op_sel_hi:[1,0]
	v_pk_mul_f32 v[24:25], v[24:25], v[32:33] op_sel_hi:[1,0]
	v_pk_mul_f32 v[22:23], v[22:23], v[32:33] op_sel_hi:[1,0]
	v_pk_mul_f32 v[20:21], v[20:21], v[32:33] op_sel_hi:[1,0]
	v_pk_mul_f32 v[18:19], v[18:19], v[32:33] op_sel_hi:[1,0]
	v_pk_mul_f32 v[16:17], v[16:17], v[32:33] op_sel_hi:[1,0]
	v_cvt_pk_bf16_f32 v39, v115, v116
	v_cvt_pk_bf16_f32 v40, v117, v114
	v_cvt_pk_bf16_f32 v41, v119, v118
	v_fma_f32 v128, v61, s6, v229
	v_pk_mul_f32 v[14:15], v[14:15], v[32:33] op_sel_hi:[1,0]
	s_waitcnt lgkmcnt(2)
	v_mfma_f32_32x32x16_bf16 v[16:31], v[34:37], v[38:41], v[16:31]
	ds_read_b64_tr_b16 v[34:35], v224 offset:10240
	ds_read_b64_tr_b16 v[36:37], v224 offset:11264
	v_mul_f32_e64 v12, v12, v32
	v_mul_f32_e64 v13, v13, v32
	v_mul_f32_e64 v10, v10, v32
	v_mul_f32_e64 v11, v11, v32
	v_pk_mul_f32 v[8:9], v[8:9], v[32:33] op_sel_hi:[1,0]
	v_pk_mul_f32 v[6:7], v[6:7], v[32:33] op_sel_hi:[1,0]
	v_pk_mul_f32 v[4:5], v[4:5], v[32:33] op_sel_hi:[1,0]
	v_pk_mul_f32 v[2:3], v[2:3], v[32:33] op_sel_hi:[1,0]
	v_pk_mul_f32 v[0:1], v[0:1], v[32:33] op_sel_hi:[1,0]
	v_cmp_lt_f32_e32 vcc, s86, v61
	v_fma_f32 v61, v62, s6, v229
	s_waitcnt lgkmcnt(2)
	v_mfma_f32_32x32x16_bf16 v[0:15], v[42:45], v[38:41], v[0:15]
	v_mov_b32_e32 v38, v128
	v_exp_f32_e32 v113, v38
	v_cvt_pk_bf16_f32 v38, v121, v120
	v_cvt_pk_bf16_f32 v39, v123, v122
	v_cvt_pk_bf16_f32 v40, v125, v124
	v_cvt_pk_bf16_f32 v41, v46, v47
	ds_read_b64_tr_b16 v[42:43], v225 offset:10240
	ds_read_b64_tr_b16 v[44:45], v225 offset:11264
	v_cndmask_b32_e32 v46, 0, v113, vcc
	s_waitcnt lgkmcnt(2)
	v_mfma_f32_32x32x16_bf16 v[16:31], v[34:37], v[38:41], v[16:31]
	v_exp_f32_e32 v34, v127
	v_cmp_lt_f32_e32 vcc, s86, v60
	s_nop 1
	v_cndmask_b32_e32 v47, 0, v34, vcc
	ds_read_b64_tr_b16 v[34:35], v224 offset:12288
	ds_read_b64_tr_b16 v[36:37], v224 offset:13312
	v_cmp_lt_f32_e32 vcc, s86, v63
	s_waitcnt lgkmcnt(2)
	v_mfma_f32_32x32x16_bf16 v[0:15], v[42:45], v[38:41], v[0:15]
	ds_read_b64_tr_b16 v[42:43], v225 offset:12288
	ds_read_b64_tr_b16 v[44:45], v225 offset:13312
	v_cvt_pk_bf16_f32 v38, v48, v49
	v_cvt_pk_bf16_f32 v39, v50, v51
	v_cvt_pk_bf16_f32 v40, v52, v53
	v_cvt_pk_bf16_f32 v41, v54, v55
	v_add_f32_e32 v60, v47, v126
	v_add_f32_e32 v60, v46, v60
	s_waitcnt lgkmcnt(2)
	v_mfma_f32_32x32x16_bf16 v[16:31], v[34:37], v[38:41], v[16:31]
	v_fma_f32 v34, v63, s6, v229
	s_nop 0
	v_exp_f32_e32 v34, v34
	v_mov_b32_e32 v35, v61
	v_exp_f32_e32 v48, v35
	v_cndmask_b32_e32 v49, 0, v34, vcc
	s_waitcnt lgkmcnt(0)
	v_mfma_f32_32x32x16_bf16 v[0:15], v[42:45], v[38:41], v[0:15]
	ds_read_b64_tr_b16 v[34:35], v224 offset:14336
	ds_read_b64_tr_b16 v[36:37], v224 offset:15360
	ds_read_b64_tr_b16 v[42:43], v225 offset:14336
	ds_read_b64_tr_b16 v[44:45], v225 offset:15360
	v_cmp_lt_f32_e32 vcc, s86, v62
	v_cvt_pk_bf16_f32 v38, v56, v57
	v_cvt_pk_bf16_f32 v39, v58, v59
	v_cndmask_b32_e32 v41, 0, v48, vcc
	v_add_f32_e32 v48, v41, v60
	v_cvt_pk_bf16_f32 v40, v47, v46
	v_cvt_pk_bf16_f32 v41, v41, v49
	s_waitcnt lgkmcnt(2)
	s_nop 0
	v_mfma_f32_32x32x16_bf16 v[16:31], v[34:37], v[38:41], v[16:31]
	v_add_f32_e32 v34, v49, v48
	ds_bpermute_b32 v35, v101, v34
	s_waitcnt lgkmcnt(0)
	v_add_f32_e32 v34, v34, v35
	v_mfma_f32_32x32x16_bf16 v[0:15], v[42:45], v[38:41], v[0:15]
	v_fmac_f32_e32 v34, v107, v32
	s_cbranch_scc1 .LBB0_243
	v_div_scale_f32 v32, s[0:1], v34, v34, 1.0
	v_rcp_f32_e32 v33, v32
	v_div_scale_f32 v35, vcc, 1.0, v34, 1.0
	v_readlane_b32 s0, v254, 43
	v_fma_f32 v36, -v32, v33, 1.0
	v_fmac_f32_e32 v33, v36, v33
	v_mul_f32_e32 v36, v35, v33
	v_fma_f32 v37, -v32, v36, v35
	v_fmac_f32_e32 v36, v37, v33
	v_fma_f32 v32, -v32, v36, v35
	v_div_fmas_f32 v32, v32, v33, v36
	v_div_fixup_f32 v32, v32, v34, 1.0
	v_lshlrev_b64 v[34:35], 11, v[96:97]
	v_readlane_b32 s1, v254, 44
	s_lshl_b32 s92, s4, 1
	v_pk_mul_f32 v[16:17], v[16:17], v[32:33] op_sel_hi:[1,0]
	v_lshl_add_u64 v[34:35], s[0:1], 0, v[34:35]
	v_lshl_add_u64 v[34:35], v[34:35], 0, s[92:93]
	v_pk_mul_f32 v[18:19], v[18:19], v[32:33] op_sel_hi:[1,0]
	v_lshlrev_b32_e32 v128, 3, v100
	v_cvt_pk_bf16_f32 v16, v16, v17
	v_cvt_pk_bf16_f32 v17, v18, v19
	v_lshl_add_u64 v[18:19], v[34:35], 0, v[128:129]
	s_mov_b64 s[0:1], 0x153ca200
	v_lshl_add_u64 v[34:35], v[18:19], 0, s[0:1]
	s_mov_b32 s0, 0x153ca000
	v_add_co_u32_e32 v18, vcc, s0, v18
	v_pk_mul_f32 v[0:1], v[0:1], v[32:33] op_sel_hi:[1,0]
	v_pk_mul_f32 v[2:3], v[2:3], v[32:33] op_sel_hi:[1,0]
	v_addc_co_u32_e32 v19, vcc, 0, v19, vcc
	v_cvt_pk_bf16_f32 v0, v0, v1
	v_cvt_pk_bf16_f32 v1, v2, v3
	global_store_dwordx2 v[18:19], v[16:17], off offset:512
	v_pk_mul_f32 v[16:17], v[20:21], v[32:33] op_sel_hi:[1,0]
	v_pk_mul_f32 v[18:19], v[22:23], v[32:33] op_sel_hi:[1,0]
	global_store_dwordx2 v[34:35], v[0:1], off offset:64
	v_pk_mul_f32 v[0:1], v[4:5], v[32:33] op_sel_hi:[1,0]
	v_pk_mul_f32 v[2:3], v[6:7], v[32:33] op_sel_hi:[1,0]
	v_cvt_pk_bf16_f32 v16, v16, v17
	v_cvt_pk_bf16_f32 v17, v18, v19
	v_cvt_pk_bf16_f32 v0, v0, v1
	v_cvt_pk_bf16_f32 v1, v2, v3
	global_store_dwordx2 v[34:35], v[16:17], off offset:16
	v_pk_mul_f32 v[16:17], v[24:25], v[32:33] op_sel_hi:[1,0]
	v_pk_mul_f32 v[18:19], v[26:27], v[32:33] op_sel_hi:[1,0]
	global_store_dwordx2 v[34:35], v[0:1], off offset:80
	v_pk_mul_f32 v[0:1], v[8:9], v[32:33] op_sel_hi:[1,0]
	v_pk_mul_f32 v[2:3], v[10:11], v[32:33] op_sel_hi:[1,0]
	v_cvt_pk_bf16_f32 v16, v16, v17
	v_cvt_pk_bf16_f32 v17, v18, v19
	v_cvt_pk_bf16_f32 v0, v0, v1
	v_cvt_pk_bf16_f32 v1, v2, v3
	global_store_dwordx2 v[34:35], v[16:17], off offset:32
	v_pk_mul_f32 v[16:17], v[28:29], v[32:33] op_sel_hi:[1,0]
	v_pk_mul_f32 v[18:19], v[30:31], v[32:33] op_sel_hi:[1,0]
	global_store_dwordx2 v[34:35], v[0:1], off offset:96
	v_pk_mul_f32 v[0:1], v[12:13], v[32:33] op_sel_hi:[1,0]
	v_pk_mul_f32 v[2:3], v[14:15], v[32:33] op_sel_hi:[1,0]
	v_cvt_pk_bf16_f32 v16, v16, v17
	v_cvt_pk_bf16_f32 v17, v18, v19
	v_cvt_pk_bf16_f32 v0, v0, v1
	v_cvt_pk_bf16_f32 v1, v2, v3
	global_store_dwordx2 v[34:35], v[16:17], off offset:48
	global_store_dwordx2 v[34:35], v[0:1], off offset:112
	s_barrier
